# P1 QK-norm epilogue: the 16 ds_bpermute round trips of the per-row sum-of-squares reduction (xor 16, xor 32) replaced by copy + v_permlane16_swap / v_permlane32_swap
# baseline (speedup 1.0000x reference)
.LBB0_199:
	s_andn2_b64 vcc, exec, s[68:69]
	s_cbranch_vccnz .LBB0_201
	s_cmp_eq_u32 s19, 4
	s_cselect_b64 vcc, -1, 0
	v_readlane_b32 s36, v252, 8
	s_and_b64 s[52:53], vcc, exec
	v_readlane_b32 s48, v252, 20
	v_readlane_b32 s49, v252, 21
	v_readlane_b32 s50, v252, 22
	v_readlane_b32 s51, v252, 23
	s_cselect_b32 s53, s49, s51
	s_cselect_b32 s52, s48, s50
	global_load_dwordx4 v[140:143], v187, s[52:53]
	global_load_dwordx4 v[136:139], v187, s[52:53] offset:16
	global_load_dwordx4 v[128:131], v187, s[52:53] offset:144
	global_load_dwordx4 v[132:135], v187, s[52:53] offset:128
	v_and_b32_e32 v169, 64, v189
	v_xor_b32_e32 v168, 16, v189
	v_add_u32_e32 v169, 64, v169
	v_cndmask_b32_e32 v191, 1.0, v188, vcc
	v_cmp_lt_i32_e32 vcc, v168, v169
	v_pk_mul_f32 v[170:171], v[124:125], v[124:125]
	v_pk_mul_f32 v[196:197], v[108:109], v[108:109]
	v_cndmask_b32_e32 v168, v189, v168, vcc
	v_lshlrev_b32_e32 v193, 2, v168
	v_xor_b32_e32 v168, 32, v189
	v_cmp_lt_i32_e32 vcc, v168, v169
	v_readlane_b32 s37, v252, 9
	v_readlane_b32 s38, v252, 10
	v_cndmask_b32_e32 v168, v189, v168, vcc
	v_lshlrev_b32_e32 v192, 2, v168
	v_pk_mul_f32 v[168:169], v[126:127], v[126:127]
	v_readlane_b32 s39, v252, 11
	v_pk_mov_b32 v[172:173], v[170:171], v[168:169] op_sel:[1,0]
	v_mov_b32_e32 v171, v169
	v_pk_add_f32 v[168:169], v[172:173], v[170:171]
	v_pk_mul_f32 v[170:171], v[122:123], v[122:123]
	v_pk_mul_f32 v[172:173], v[120:121], v[120:121]
	v_pk_add_f32 v[168:169], v[168:169], v[168:169] op_sel:[0,1] op_sel_hi:[1,0]
	v_pk_mov_b32 v[194:195], v[172:173], v[170:171] op_sel:[1,0]
	v_mov_b32_e32 v173, v171
	v_pk_add_f32 v[170:171], v[194:195], v[172:173]
	v_mul_f32_e32 v172, v112, v112
	v_mul_f32_e32 v173, v113, v113
	v_pk_add_f32 v[170:171], v[170:171], v[170:171] op_sel:[0,1] op_sel_hi:[1,0]
	v_mov_b32_e32 v169, v172
	v_mov_b32_e32 v171, v173
	v_pk_add_f32 v[168:169], v[168:169], v[170:171]
	v_mul_f32_e32 v170, v117, v117
	v_mul_f32_e32 v172, v119, v119
	v_mul_f32_e32 v194, v114, v114
	v_mul_f32_e32 v195, v115, v115
	v_pk_fma_f32 v[170:171], v[116:117], v[116:117], v[170:171] op_sel_hi:[1,1,0]
	v_pk_fma_f32 v[172:173], v[118:119], v[118:119], v[172:173] op_sel_hi:[1,1,0]
	v_mov_b32_e32 v171, v194
	v_mov_b32_e32 v173, v195
	v_pk_mul_f32 v[194:195], v[110:111], v[110:111]
	v_pk_add_f32 v[170:171], v[170:171], v[172:173]
	v_pk_mov_b32 v[198:199], v[196:197], v[194:195] op_sel:[1,0]
	v_mov_b32_e32 v197, v195
	v_pk_add_f32 v[194:195], v[198:199], v[196:197]
	v_pk_mul_f32 v[196:197], v[106:107], v[106:107]
	v_pk_mul_f32 v[198:199], v[104:105], v[104:105]
	v_pk_add_f32 v[194:195], v[194:195], v[194:195] op_sel:[0,1] op_sel_hi:[1,0]
	v_pk_mov_b32 v[200:201], v[198:199], v[196:197] op_sel:[1,0]
	v_mov_b32_e32 v199, v197
	v_pk_add_f32 v[196:197], v[200:201], v[198:199]
	v_mul_f32_e32 v198, v96, v96
	v_mul_f32_e32 v199, v97, v97
	v_pk_add_f32 v[196:197], v[196:197], v[196:197] op_sel:[0,1] op_sel_hi:[1,0]
	v_mov_b32_e32 v195, v198
	v_mov_b32_e32 v197, v199
	v_pk_add_f32 v[194:195], v[194:195], v[196:197]
	v_mul_f32_e32 v196, v101, v101
	v_mul_f32_e32 v198, v103, v103
	v_mul_f32_e32 v200, v98, v98
	v_mul_f32_e32 v201, v99, v99
	v_pk_fma_f32 v[196:197], v[100:101], v[100:101], v[196:197] op_sel_hi:[1,1,0]
	v_pk_fma_f32 v[198:199], v[102:103], v[102:103], v[198:199] op_sel_hi:[1,1,0]
	v_mov_b32_e32 v197, v200
	v_mov_b32_e32 v199, v201
	v_pk_add_f32 v[196:197], v[196:197], v[198:199]
	v_pk_add_f32 v[170:171], v[168:169], v[170:171]
	v_pk_add_f32 v[194:195], v[194:195], v[196:197]
	v_mov_b32_e32 v197, v170
	v_mov_b32_e32 v196, v194
	v_mov_b32_e32 v170, v195
	v_pk_add_f32 v[194:195], v[196:197], v[170:171]
	v_mov_b32_e32 v197, v195
	v_mov_b32_e32 v196, v194
	s_nop 0
	v_permlane16_swap_b32_e32 v197, v195
	v_permlane16_swap_b32_e32 v196, v194
	v_mov_b64_e32 v[168:169], s[20:21]
	v_mad_i64_i32 v[172:173], s[52:53], v190, s87, v[168:169]
	v_lshlrev_b64 v[170:171], 1, v[154:155]
	v_lshl_add_u64 v[198:199], v[172:173], 0, v[170:171]
	s_waitcnt lgkmcnt(0)
	v_pk_add_f32 v[172:173], v[194:195], v[196:197]
	v_mov_b32_e32 v195, v173
	v_mov_b32_e32 v194, v172
	s_nop 0
	v_permlane32_swap_b32_e32 v195, v173
	v_permlane32_swap_b32_e32 v194, v172
	s_mov_b32 s52, 0x358637bd
	s_waitcnt vmcnt(0)
	v_pk_mul_f32 v[200:201], v[126:127], v[142:143]
	v_pk_mul_f32 v[202:203], v[124:125], v[140:141]
	v_pk_mul_f32 v[196:197], v[122:123], v[138:139]
	s_waitcnt lgkmcnt(0)
	v_pk_add_f32 v[194:195], v[172:173], v[194:195]
	v_mov_b64_e32 v[172:173], s[52:53]
	v_pk_fma_f32 v[210:211], v[194:195], s[16:17], v[172:173] op_sel_hi:[1,0,0]
	v_pk_mul_f32 v[204:205], v[120:121], v[136:137]
	v_mul_f32_e32 v194, 0x4b800000, v211
	v_cmp_gt_f32_e32 vcc, s88, v211
	v_pk_mul_f32 v[206:207], v[118:119], v[134:135]
	v_pk_mul_f32 v[208:209], v[116:117], v[132:133]
	v_cndmask_b32_e32 v194, v211, v194, vcc
	v_rsq_f32_e32 v194, v194
	v_pk_mul_f32 v[212:213], v[114:115], v[130:131]
	v_pk_mul_f32 v[214:215], v[112:113], v[128:129]
	v_or_b32_e32 v211, 16, v190
	v_mul_f32_e32 v195, 0x45800000, v194
	v_cndmask_b32_e32 v194, v194, v195, vcc
	v_mul_f32_e32 v216, v191, v194
	v_pk_mul_f32 v[200:201], v[200:201], v[216:217] op_sel_hi:[1,0]
	v_pk_mul_f32 v[194:195], v[202:203], v[216:217] op_sel_hi:[1,0]
	v_pk_mul_f32 v[202:203], v[196:197], v[216:217] op_sel_hi:[1,0]
	v_pk_mul_f32 v[196:197], v[204:205], v[216:217] op_sel_hi:[1,0]
	v_cvt_pk_bf16_f32 v194, v194, v195
	v_cvt_pk_bf16_f32 v195, v200, v201
	v_cvt_pk_bf16_f32 v196, v196, v197
	v_cvt_pk_bf16_f32 v197, v202, v203
	global_store_dwordx4 v[198:199], v[194:197], off
	v_cmp_gt_f32_e32 vcc, s88, v210
	v_pk_mul_f32 v[200:201], v[212:213], v[216:217] op_sel_hi:[1,0]
	v_pk_mul_f32 v[196:197], v[206:207], v[216:217] op_sel_hi:[1,0]
	v_pk_mul_f32 v[194:195], v[208:209], v[216:217] op_sel_hi:[1,0]
	v_pk_mul_f32 v[202:203], v[214:215], v[216:217] op_sel_hi:[1,0]
	v_cvt_pk_bf16_f32 v194, v194, v195
	v_cvt_pk_bf16_f32 v195, v196, v197
	v_mul_f32_e32 v196, 0x4b800000, v210
	v_cndmask_b32_e32 v196, v210, v196, vcc
	v_rsq_f32_e32 v204, v196
	v_cvt_pk_bf16_f32 v196, v202, v203
	v_cvt_pk_bf16_f32 v197, v200, v201
	global_store_dwordx4 v[198:199], v[194:197], off offset:64
	v_pk_mul_f32 v[208:209], v[86:87], v[134:135]
	v_pk_mul_f32 v[214:215], v[82:83], v[130:131]
	v_mul_f32_e32 v194, 0x45800000, v204
	v_cndmask_b32_e32 v194, v204, v194, vcc
	v_mul_f32_e32 v198, v191, v194
	v_mad_i64_i32 v[194:195], s[52:53], v211, s87, v[168:169]
	v_lshl_add_u64 v[200:201], v[194:195], 0, v[170:171]
	v_pk_mul_f32 v[194:195], v[110:111], v[142:143]
	v_pk_mul_f32 v[196:197], v[108:109], v[140:141]
	v_pk_mul_f32 v[202:203], v[194:195], v[198:199] op_sel_hi:[1,0]
	v_pk_mul_f32 v[194:195], v[196:197], v[198:199] op_sel_hi:[1,0]
	v_pk_mul_f32 v[196:197], v[106:107], v[138:139]
	v_pk_mul_f32 v[204:205], v[104:105], v[136:137]
	v_pk_mul_f32 v[206:207], v[196:197], v[198:199] op_sel_hi:[1,0]
	v_pk_mul_f32 v[196:197], v[204:205], v[198:199] op_sel_hi:[1,0]
	v_cvt_pk_bf16_f32 v194, v194, v195
	v_cvt_pk_bf16_f32 v195, v202, v203
	v_cvt_pk_bf16_f32 v196, v196, v197
	v_cvt_pk_bf16_f32 v197, v206, v207
	global_store_dwordx4 v[200:201], v[194:197], off
	v_pk_mul_f32 v[204:205], v[96:97], v[128:129]
	v_pk_mul_f32 v[210:211], v[84:85], v[132:133]
	v_pk_mul_f32 v[194:195], v[102:103], v[134:135]
	v_pk_mul_f32 v[196:197], v[100:101], v[132:133]
	v_pk_mul_f32 v[202:203], v[194:195], v[198:199] op_sel_hi:[1,0]
	v_pk_mul_f32 v[194:195], v[196:197], v[198:199] op_sel_hi:[1,0]
	v_pk_mul_f32 v[196:197], v[98:99], v[130:131]
	v_cvt_pk_bf16_f32 v194, v194, v195
	v_pk_mul_f32 v[206:207], v[196:197], v[198:199] op_sel_hi:[1,0]
	v_pk_mul_f32 v[196:197], v[204:205], v[198:199] op_sel_hi:[1,0]
	v_cvt_pk_bf16_f32 v195, v202, v203
	v_cvt_pk_bf16_f32 v196, v196, v197
	v_cvt_pk_bf16_f32 v197, v206, v207
	global_store_dwordx4 v[200:201], v[194:197], off offset:64
	v_or_b32_e32 v204, 32, v190
	v_pk_mul_f32 v[206:207], v[88:89], v[136:137]
	v_pk_mul_f32 v[194:195], v[94:95], v[94:95]
	v_pk_mul_f32 v[196:197], v[92:93], v[92:93]
	v_pk_mul_f32 v[216:217], v[80:81], v[128:129]
	v_pk_mov_b32 v[198:199], v[196:197], v[194:195] op_sel:[1,0]
	v_mov_b32_e32 v197, v195
	v_pk_add_f32 v[194:195], v[198:199], v[196:197]
	v_pk_mul_f32 v[196:197], v[90:91], v[90:91]
	v_pk_mul_f32 v[198:199], v[88:89], v[88:89]
	v_pk_add_f32 v[194:195], v[194:195], v[194:195] op_sel:[0,1] op_sel_hi:[1,0]
	v_pk_mov_b32 v[200:201], v[198:199], v[196:197] op_sel:[1,0]
	v_mov_b32_e32 v199, v197
	v_pk_add_f32 v[196:197], v[200:201], v[198:199]
	v_mul_f32_e32 v198, v80, v80
	v_mul_f32_e32 v199, v81, v81
	v_pk_add_f32 v[196:197], v[196:197], v[196:197] op_sel:[0,1] op_sel_hi:[1,0]
	v_mov_b32_e32 v195, v198
	v_mov_b32_e32 v197, v199
	v_pk_add_f32 v[194:195], v[194:195], v[196:197]
	v_mul_f32_e32 v196, v85, v85
	v_mul_f32_e32 v198, v87, v87
	v_mul_f32_e32 v200, v82, v82
	v_mul_f32_e32 v201, v83, v83
	v_pk_fma_f32 v[196:197], v[84:85], v[84:85], v[196:197] op_sel_hi:[1,1,0]
	v_pk_fma_f32 v[198:199], v[86:87], v[86:87], v[198:199] op_sel_hi:[1,1,0]
	v_mov_b32_e32 v197, v200
	v_mov_b32_e32 v199, v201
	v_pk_add_f32 v[196:197], v[196:197], v[198:199]
	v_pk_mul_f32 v[198:199], v[76:77], v[76:77]
	v_pk_add_f32 v[194:195], v[194:195], v[196:197]
	v_pk_mul_f32 v[196:197], v[78:79], v[78:79]
	v_readlane_b32 s40, v252, 12
	v_pk_mov_b32 v[200:201], v[198:199], v[196:197] op_sel:[1,0]
	v_mov_b32_e32 v199, v197
	v_pk_add_f32 v[196:197], v[200:201], v[198:199]
	v_pk_mul_f32 v[198:199], v[74:75], v[74:75]
	v_pk_mul_f32 v[200:201], v[72:73], v[72:73]
	v_pk_add_f32 v[196:197], v[196:197], v[196:197] op_sel:[0,1] op_sel_hi:[1,0]
	v_pk_mov_b32 v[202:203], v[200:201], v[198:199] op_sel:[1,0]
	v_mov_b32_e32 v201, v199
	v_pk_add_f32 v[198:199], v[202:203], v[200:201]
	v_mul_f32_e32 v200, v64, v64
	v_mul_f32_e32 v201, v65, v65
	v_pk_add_f32 v[198:199], v[198:199], v[198:199] op_sel:[0,1] op_sel_hi:[1,0]
	v_mov_b32_e32 v197, v200
	v_mov_b32_e32 v199, v201
	v_pk_add_f32 v[196:197], v[196:197], v[198:199]
	v_mul_f32_e32 v198, v69, v69
	v_mul_f32_e32 v200, v71, v71
	v_mul_f32_e32 v202, v66, v66
	v_mul_f32_e32 v203, v67, v67
	v_pk_fma_f32 v[198:199], v[68:69], v[68:69], v[198:199] op_sel_hi:[1,1,0]
	v_pk_fma_f32 v[200:201], v[70:71], v[70:71], v[200:201] op_sel_hi:[1,1,0]
	v_mov_b32_e32 v199, v202
	v_mov_b32_e32 v201, v203
	v_pk_add_f32 v[198:199], v[198:199], v[200:201]
	v_pk_mul_f32 v[200:201], v[94:95], v[142:143]
	v_pk_add_f32 v[196:197], v[196:197], v[198:199]
	v_mov_b32_e32 v199, v194
	v_mov_b32_e32 v198, v196
	v_mov_b32_e32 v194, v197
	v_pk_add_f32 v[194:195], v[198:199], v[194:195]
	v_mov_b32_e32 v197, v195
	v_mov_b32_e32 v196, v194
	s_nop 0
	v_permlane16_swap_b32_e32 v197, v195
	v_permlane16_swap_b32_e32 v196, v194
	v_mad_i64_i32 v[198:199], s[52:53], v204, s87, v[168:169]
	v_pk_mul_f32 v[202:203], v[92:93], v[140:141]
	v_pk_mul_f32 v[204:205], v[90:91], v[138:139]
	s_waitcnt lgkmcnt(0)
	v_pk_add_f32 v[194:195], v[194:195], v[196:197]
	v_mov_b32_e32 v197, v195
	v_mov_b32_e32 v196, v194
	s_nop 0
	v_permlane32_swap_b32_e32 v197, v195
	v_permlane32_swap_b32_e32 v196, v194
	v_lshl_add_u64 v[198:199], v[198:199], 0, v[170:171]
	v_readlane_b32 s41, v252, 13
	v_readlane_b32 s42, v252, 14
	v_readlane_b32 s43, v252, 15
	s_waitcnt lgkmcnt(0)
	v_pk_add_f32 v[194:195], v[194:195], v[196:197]
	v_readlane_b32 s44, v252, 16
	v_pk_fma_f32 v[212:213], v[194:195], s[16:17], v[172:173] op_sel_hi:[1,0,0]
	v_readlane_b32 s45, v252, 17
	v_mul_f32_e32 v194, 0x4b800000, v213
	v_cmp_gt_f32_e32 vcc, s88, v213
	v_readlane_b32 s46, v252, 18
	v_readlane_b32 s47, v252, 19
	v_cndmask_b32_e32 v194, v213, v194, vcc
	v_rsq_f32_e32 v194, v194
	v_or_b32_e32 v213, 48, v190
	v_mul_f32_e32 v195, 0x45800000, v194
	v_cndmask_b32_e32 v194, v194, v195, vcc
	v_mul_f32_e32 v218, v191, v194
	v_pk_mul_f32 v[196:197], v[200:201], v[218:219] op_sel_hi:[1,0]
	v_pk_mul_f32 v[194:195], v[202:203], v[218:219] op_sel_hi:[1,0]
	v_pk_mul_f32 v[200:201], v[204:205], v[218:219] op_sel_hi:[1,0]
	v_pk_mul_f32 v[202:203], v[206:207], v[218:219] op_sel_hi:[1,0]
	v_cvt_pk_bf16_f32 v194, v194, v195
	v_cvt_pk_bf16_f32 v195, v196, v197
	v_cvt_pk_bf16_f32 v196, v202, v203
	v_cvt_pk_bf16_f32 v197, v200, v201
	global_store_dwordx4 v[198:199], v[194:197], off
	v_cmp_gt_f32_e32 vcc, s88, v212
	v_pk_mul_f32 v[200:201], v[214:215], v[218:219] op_sel_hi:[1,0]
	v_pk_mul_f32 v[196:197], v[208:209], v[218:219] op_sel_hi:[1,0]
	v_pk_mul_f32 v[194:195], v[210:211], v[218:219] op_sel_hi:[1,0]
	v_pk_mul_f32 v[202:203], v[216:217], v[218:219] op_sel_hi:[1,0]
	v_cvt_pk_bf16_f32 v194, v194, v195
	v_cvt_pk_bf16_f32 v195, v196, v197
	v_mul_f32_e32 v196, 0x4b800000, v212
	v_cndmask_b32_e32 v196, v212, v196, vcc
	v_rsq_f32_e32 v204, v196
	v_cvt_pk_bf16_f32 v196, v202, v203
	v_cvt_pk_bf16_f32 v197, v200, v201
	global_store_dwordx4 v[198:199], v[194:197], off offset:64
	v_pk_mul_f32 v[208:209], v[54:55], v[134:135]
	v_pk_mul_f32 v[210:211], v[52:53], v[132:133]
	v_mul_f32_e32 v194, 0x45800000, v204
	v_cndmask_b32_e32 v194, v204, v194, vcc
	v_mul_f32_e32 v198, v191, v194
	v_mad_i64_i32 v[194:195], s[52:53], v213, s87, v[168:169]
	v_lshl_add_u64 v[200:201], v[194:195], 0, v[170:171]
	v_pk_mul_f32 v[194:195], v[78:79], v[142:143]
	v_pk_mul_f32 v[196:197], v[76:77], v[140:141]
	v_pk_mul_f32 v[202:203], v[194:195], v[198:199] op_sel_hi:[1,0]
	v_pk_mul_f32 v[194:195], v[196:197], v[198:199] op_sel_hi:[1,0]
	v_pk_mul_f32 v[196:197], v[74:75], v[138:139]
	v_pk_mul_f32 v[204:205], v[72:73], v[136:137]
	v_pk_mul_f32 v[206:207], v[196:197], v[198:199] op_sel_hi:[1,0]
	v_pk_mul_f32 v[196:197], v[204:205], v[198:199] op_sel_hi:[1,0]
	v_cvt_pk_bf16_f32 v194, v194, v195
	v_cvt_pk_bf16_f32 v195, v202, v203
	v_cvt_pk_bf16_f32 v196, v196, v197
	v_cvt_pk_bf16_f32 v197, v206, v207
	global_store_dwordx4 v[200:201], v[194:197], off
	v_pk_mul_f32 v[204:205], v[64:65], v[128:129]
	v_pk_mul_f32 v[214:215], v[50:51], v[130:131]
	v_pk_mul_f32 v[194:195], v[70:71], v[134:135]
	v_pk_mul_f32 v[196:197], v[68:69], v[132:133]
	v_pk_mul_f32 v[202:203], v[194:195], v[198:199] op_sel_hi:[1,0]
	v_pk_mul_f32 v[194:195], v[196:197], v[198:199] op_sel_hi:[1,0]
	v_pk_mul_f32 v[196:197], v[66:67], v[130:131]
	v_cvt_pk_bf16_f32 v194, v194, v195
	v_pk_mul_f32 v[206:207], v[196:197], v[198:199] op_sel_hi:[1,0]
	v_pk_mul_f32 v[196:197], v[204:205], v[198:199] op_sel_hi:[1,0]
	v_cvt_pk_bf16_f32 v195, v202, v203
	v_cvt_pk_bf16_f32 v196, v196, v197
	v_cvt_pk_bf16_f32 v197, v206, v207
	global_store_dwordx4 v[200:201], v[194:197], off offset:64
	v_add_u32_e32 v204, 0x80, v190
	v_pk_mul_f32 v[206:207], v[56:57], v[136:137]
	v_pk_mul_f32 v[194:195], v[62:63], v[62:63]
	v_pk_mul_f32 v[196:197], v[60:61], v[60:61]
	v_pk_mul_f32 v[216:217], v[48:49], v[128:129]
	v_pk_mov_b32 v[198:199], v[196:197], v[194:195] op_sel:[1,0]
	v_mov_b32_e32 v197, v195
	v_pk_add_f32 v[194:195], v[198:199], v[196:197]
	v_pk_mul_f32 v[196:197], v[58:59], v[58:59]
	v_pk_mul_f32 v[198:199], v[56:57], v[56:57]
	v_pk_add_f32 v[194:195], v[194:195], v[194:195] op_sel:[0,1] op_sel_hi:[1,0]
	v_pk_mov_b32 v[200:201], v[198:199], v[196:197] op_sel:[1,0]
	v_mov_b32_e32 v199, v197
	v_pk_add_f32 v[196:197], v[200:201], v[198:199]
	v_mul_f32_e32 v198, v48, v48
	v_mul_f32_e32 v199, v49, v49
	v_pk_add_f32 v[196:197], v[196:197], v[196:197] op_sel:[0,1] op_sel_hi:[1,0]
	v_mov_b32_e32 v195, v198
	v_mov_b32_e32 v197, v199
	v_pk_add_f32 v[194:195], v[194:195], v[196:197]
	v_mul_f32_e32 v196, v53, v53
	v_mul_f32_e32 v198, v55, v55
	v_mul_f32_e32 v200, v50, v50
	v_mul_f32_e32 v201, v51, v51
	v_pk_fma_f32 v[196:197], v[52:53], v[52:53], v[196:197] op_sel_hi:[1,1,0]
	v_pk_fma_f32 v[198:199], v[54:55], v[54:55], v[198:199] op_sel_hi:[1,1,0]
	v_mov_b32_e32 v197, v200
	v_mov_b32_e32 v199, v201
	v_pk_add_f32 v[196:197], v[196:197], v[198:199]
	v_pk_mul_f32 v[198:199], v[44:45], v[44:45]
	v_pk_add_f32 v[194:195], v[194:195], v[196:197]
	v_pk_mul_f32 v[196:197], v[46:47], v[46:47]
	s_nop 0
	v_pk_mov_b32 v[200:201], v[198:199], v[196:197] op_sel:[1,0]
	v_mov_b32_e32 v199, v197
	v_pk_add_f32 v[196:197], v[200:201], v[198:199]
	v_pk_mul_f32 v[198:199], v[42:43], v[42:43]
	v_pk_mul_f32 v[200:201], v[40:41], v[40:41]
	v_pk_add_f32 v[196:197], v[196:197], v[196:197] op_sel:[0,1] op_sel_hi:[1,0]
	v_pk_mov_b32 v[202:203], v[200:201], v[198:199] op_sel:[1,0]
	v_mov_b32_e32 v201, v199
	v_pk_add_f32 v[198:199], v[202:203], v[200:201]
	v_mul_f32_e32 v200, v32, v32
	v_mul_f32_e32 v201, v33, v33
	v_pk_add_f32 v[198:199], v[198:199], v[198:199] op_sel:[0,1] op_sel_hi:[1,0]
	v_mov_b32_e32 v197, v200
	v_mov_b32_e32 v199, v201
	v_pk_add_f32 v[196:197], v[196:197], v[198:199]
	v_mul_f32_e32 v198, v37, v37
	v_mul_f32_e32 v200, v39, v39
	v_mul_f32_e32 v202, v34, v34
	v_mul_f32_e32 v203, v35, v35
	v_pk_fma_f32 v[198:199], v[36:37], v[36:37], v[198:199] op_sel_hi:[1,1,0]
	v_pk_fma_f32 v[200:201], v[38:39], v[38:39], v[200:201] op_sel_hi:[1,1,0]
	v_mov_b32_e32 v199, v202
	v_mov_b32_e32 v201, v203
	v_pk_add_f32 v[198:199], v[198:199], v[200:201]
	v_pk_mul_f32 v[200:201], v[62:63], v[142:143]
	v_pk_add_f32 v[196:197], v[196:197], v[198:199]
	v_mov_b32_e32 v199, v194
	v_mov_b32_e32 v198, v196
	v_mov_b32_e32 v194, v197
	v_pk_add_f32 v[194:195], v[198:199], v[194:195]
	v_mov_b32_e32 v197, v195
	v_mov_b32_e32 v196, v194
	s_nop 0
	v_permlane16_swap_b32_e32 v197, v195
	v_permlane16_swap_b32_e32 v196, v194
	v_mad_i64_i32 v[198:199], s[52:53], v204, s87, v[168:169]
	v_pk_mul_f32 v[202:203], v[60:61], v[140:141]
	v_pk_mul_f32 v[204:205], v[58:59], v[138:139]
	s_waitcnt lgkmcnt(0)
	v_pk_add_f32 v[194:195], v[194:195], v[196:197]
	v_mov_b32_e32 v197, v195
	v_mov_b32_e32 v196, v194
	s_nop 0
	v_permlane32_swap_b32_e32 v197, v195
	v_permlane32_swap_b32_e32 v196, v194
	v_lshl_add_u64 v[198:199], v[198:199], 0, v[170:171]
	s_waitcnt lgkmcnt(0)
	v_pk_add_f32 v[194:195], v[194:195], v[196:197]
	s_nop 0
	v_pk_fma_f32 v[212:213], v[194:195], s[16:17], v[172:173] op_sel_hi:[1,0,0]
	s_nop 0
	v_mul_f32_e32 v194, 0x4b800000, v213
	v_cmp_gt_f32_e32 vcc, s88, v213
	s_nop 1
	v_cndmask_b32_e32 v194, v213, v194, vcc
	v_rsq_f32_e32 v194, v194
	v_add_u32_e32 v213, 0x90, v190
	v_mul_f32_e32 v195, 0x45800000, v194
	v_cndmask_b32_e32 v194, v194, v195, vcc
	v_mul_f32_e32 v218, v191, v194
	v_pk_mul_f32 v[196:197], v[200:201], v[218:219] op_sel_hi:[1,0]
	v_pk_mul_f32 v[194:195], v[202:203], v[218:219] op_sel_hi:[1,0]
	v_pk_mul_f32 v[200:201], v[204:205], v[218:219] op_sel_hi:[1,0]
	v_pk_mul_f32 v[202:203], v[206:207], v[218:219] op_sel_hi:[1,0]
	v_cvt_pk_bf16_f32 v194, v194, v195
	v_cvt_pk_bf16_f32 v195, v196, v197
	v_cvt_pk_bf16_f32 v196, v202, v203
	v_cvt_pk_bf16_f32 v197, v200, v201
	global_store_dwordx4 v[198:199], v[194:197], off
	v_cmp_gt_f32_e32 vcc, s88, v212
	v_pk_mul_f32 v[200:201], v[214:215], v[218:219] op_sel_hi:[1,0]
	v_pk_mul_f32 v[196:197], v[208:209], v[218:219] op_sel_hi:[1,0]
	v_pk_mul_f32 v[194:195], v[210:211], v[218:219] op_sel_hi:[1,0]
	v_pk_mul_f32 v[202:203], v[216:217], v[218:219] op_sel_hi:[1,0]
	v_cvt_pk_bf16_f32 v194, v194, v195
	v_cvt_pk_bf16_f32 v195, v196, v197
	v_mul_f32_e32 v196, 0x4b800000, v212
	v_cndmask_b32_e32 v196, v212, v196, vcc
	v_rsq_f32_e32 v204, v196
	v_cvt_pk_bf16_f32 v196, v202, v203
	v_cvt_pk_bf16_f32 v197, v200, v201
	global_store_dwordx4 v[198:199], v[194:197], off offset:64
	v_add_u32_e32 v215, 0xb0, v190
	v_pk_mul_f32 v[208:209], v[20:21], v[132:133]
	v_mul_f32_e32 v194, 0x45800000, v204
	v_cndmask_b32_e32 v194, v204, v194, vcc
	v_mul_f32_e32 v198, v191, v194
	v_mad_i64_i32 v[194:195], s[52:53], v213, s87, v[168:169]
	v_lshl_add_u64 v[200:201], v[194:195], 0, v[170:171]
	v_pk_mul_f32 v[194:195], v[46:47], v[142:143]
	v_pk_mul_f32 v[196:197], v[44:45], v[140:141]
	v_pk_mul_f32 v[202:203], v[194:195], v[198:199] op_sel_hi:[1,0]
	v_pk_mul_f32 v[194:195], v[196:197], v[198:199] op_sel_hi:[1,0]
	v_pk_mul_f32 v[196:197], v[42:43], v[138:139]
	v_pk_mul_f32 v[204:205], v[40:41], v[136:137]
	v_pk_mul_f32 v[206:207], v[196:197], v[198:199] op_sel_hi:[1,0]
	v_pk_mul_f32 v[196:197], v[204:205], v[198:199] op_sel_hi:[1,0]
	v_cvt_pk_bf16_f32 v194, v194, v195
	v_cvt_pk_bf16_f32 v195, v202, v203
	v_cvt_pk_bf16_f32 v196, v196, v197
	v_cvt_pk_bf16_f32 v197, v206, v207
	global_store_dwordx4 v[200:201], v[194:197], off
	v_pk_mul_f32 v[204:205], v[32:33], v[128:129]
	v_pk_mul_f32 v[210:211], v[18:19], v[130:131]
	v_pk_mul_f32 v[194:195], v[38:39], v[134:135]
	v_pk_mul_f32 v[196:197], v[36:37], v[132:133]
	v_pk_mul_f32 v[202:203], v[194:195], v[198:199] op_sel_hi:[1,0]
	v_pk_mul_f32 v[194:195], v[196:197], v[198:199] op_sel_hi:[1,0]
	v_pk_mul_f32 v[196:197], v[34:35], v[130:131]
	v_cvt_pk_bf16_f32 v194, v194, v195
	v_pk_mul_f32 v[206:207], v[196:197], v[198:199] op_sel_hi:[1,0]
	v_pk_mul_f32 v[196:197], v[204:205], v[198:199] op_sel_hi:[1,0]
	v_cvt_pk_bf16_f32 v195, v202, v203
	v_cvt_pk_bf16_f32 v196, v196, v197
	v_cvt_pk_bf16_f32 v197, v206, v207
	global_store_dwordx4 v[200:201], v[194:197], off offset:64
	v_add_u32_e32 v204, 0xa0, v190
	v_pk_mul_f32 v[206:207], v[22:23], v[134:135]
	v_pk_mul_f32 v[194:195], v[30:31], v[30:31]
	v_pk_mul_f32 v[196:197], v[28:29], v[28:29]
	v_pk_mul_f32 v[212:213], v[16:17], v[128:129]
	v_pk_mov_b32 v[198:199], v[196:197], v[194:195] op_sel:[1,0]
	v_mov_b32_e32 v197, v195
	v_pk_add_f32 v[194:195], v[198:199], v[196:197]
	v_pk_mul_f32 v[196:197], v[26:27], v[26:27]
	v_pk_mul_f32 v[198:199], v[24:25], v[24:25]
	v_pk_add_f32 v[194:195], v[194:195], v[194:195] op_sel:[0,1] op_sel_hi:[1,0]
	v_pk_mov_b32 v[200:201], v[198:199], v[196:197] op_sel:[1,0]
	v_mov_b32_e32 v199, v197
	v_pk_add_f32 v[196:197], v[200:201], v[198:199]
	v_mul_f32_e32 v198, v16, v16
	v_mul_f32_e32 v199, v17, v17
	v_pk_add_f32 v[196:197], v[196:197], v[196:197] op_sel:[0,1] op_sel_hi:[1,0]
	v_mov_b32_e32 v195, v198
	v_mov_b32_e32 v197, v199
	v_pk_add_f32 v[194:195], v[194:195], v[196:197]
	v_mul_f32_e32 v196, v21, v21
	v_mul_f32_e32 v198, v23, v23
	v_mul_f32_e32 v200, v18, v18
	v_mul_f32_e32 v201, v19, v19
	v_pk_fma_f32 v[196:197], v[20:21], v[20:21], v[196:197] op_sel_hi:[1,1,0]
	v_pk_fma_f32 v[198:199], v[22:23], v[22:23], v[198:199] op_sel_hi:[1,1,0]
	v_mov_b32_e32 v197, v200
	v_mov_b32_e32 v199, v201
	v_pk_add_f32 v[196:197], v[196:197], v[198:199]
	v_pk_mul_f32 v[198:199], v[12:13], v[12:13]
	v_pk_add_f32 v[194:195], v[194:195], v[196:197]
	v_pk_mul_f32 v[196:197], v[14:15], v[14:15]
	v_pk_mul_f32 v[134:135], v[6:7], v[134:135]
	v_pk_mov_b32 v[200:201], v[198:199], v[196:197] op_sel:[1,0]
	v_mov_b32_e32 v199, v197
	v_pk_add_f32 v[196:197], v[200:201], v[198:199]
	v_pk_mul_f32 v[198:199], v[10:11], v[10:11]
	v_pk_mul_f32 v[200:201], v[8:9], v[8:9]
	v_pk_add_f32 v[196:197], v[196:197], v[196:197] op_sel:[0,1] op_sel_hi:[1,0]
	v_pk_mov_b32 v[202:203], v[200:201], v[198:199] op_sel:[1,0]
	v_mov_b32_e32 v201, v199
	v_pk_add_f32 v[198:199], v[202:203], v[200:201]
	v_mul_f32_e32 v200, v0, v0
	v_mul_f32_e32 v201, v1, v1
	v_pk_add_f32 v[198:199], v[198:199], v[198:199] op_sel:[0,1] op_sel_hi:[1,0]
	v_mov_b32_e32 v197, v200
	v_mov_b32_e32 v199, v201
	v_pk_add_f32 v[196:197], v[196:197], v[198:199]
	v_mul_f32_e32 v198, v5, v5
	v_mul_f32_e32 v200, v7, v7
	v_mul_f32_e32 v202, v2, v2
	v_mul_f32_e32 v203, v3, v3
	v_pk_fma_f32 v[198:199], v[4:5], v[4:5], v[198:199] op_sel_hi:[1,1,0]
	v_pk_fma_f32 v[200:201], v[6:7], v[6:7], v[200:201] op_sel_hi:[1,1,0]
	v_mov_b32_e32 v199, v202
	v_mov_b32_e32 v201, v203
	v_pk_add_f32 v[198:199], v[198:199], v[200:201]
	v_pk_mul_f32 v[200:201], v[30:31], v[142:143]
	v_pk_add_f32 v[196:197], v[196:197], v[198:199]
	v_mov_b32_e32 v199, v194
	v_mov_b32_e32 v198, v196
	v_mov_b32_e32 v194, v197
	v_pk_add_f32 v[194:195], v[198:199], v[194:195]
	v_mov_b32_e32 v197, v195
	v_mov_b32_e32 v196, v194
	s_nop 0
	v_permlane16_swap_b32_e32 v197, v195
	v_permlane16_swap_b32_e32 v196, v194
	v_mad_i64_i32 v[198:199], s[52:53], v204, s87, v[168:169]
	v_pk_mul_f32 v[202:203], v[28:29], v[140:141]
	v_pk_mul_f32 v[204:205], v[24:25], v[136:137]
	s_waitcnt lgkmcnt(0)
	v_pk_add_f32 v[194:195], v[194:195], v[196:197]
	v_mov_b32_e32 v193, v195
	v_mov_b32_e32 v192, v194
	s_nop 0
	v_permlane32_swap_b32_e32 v193, v195
	v_permlane32_swap_b32_e32 v192, v194
	v_pk_mul_f32 v[196:197], v[26:27], v[138:139]
	v_mad_i64_i32 v[168:169], s[52:53], v215, s87, v[168:169]
	v_pk_mul_f32 v[142:143], v[14:15], v[142:143]
	s_waitcnt lgkmcnt(0)
	v_pk_add_f32 v[192:193], v[194:195], v[192:193]
	v_pk_mul_f32 v[140:141], v[12:13], v[140:141]
	v_pk_fma_f32 v[172:173], v[192:193], s[16:17], v[172:173] op_sel_hi:[1,0,0]
	v_pk_mul_f32 v[138:139], v[10:11], v[138:139]
	v_mul_f32_e32 v192, 0x4b800000, v173
	v_cmp_gt_f32_e32 vcc, s88, v173
	v_pk_mul_f32 v[136:137], v[8:9], v[136:137]
	v_lshl_add_u64 v[198:199], v[198:199], 0, v[170:171]
	v_cndmask_b32_e32 v173, v173, v192, vcc
	v_rsq_f32_e32 v173, v173
	v_lshl_add_u64 v[168:169], v[168:169], 0, v[170:171]
	v_pk_mul_f32 v[132:133], v[4:5], v[132:133]
	v_pk_mul_f32 v[130:131], v[2:3], v[130:131]
	v_mul_f32_e32 v192, 0x45800000, v173
	v_cndmask_b32_e32 v173, v173, v192, vcc
	v_mul_f32_e32 v214, v191, v173
	v_mul_f32_e32 v173, 0x4b800000, v172
	v_cmp_gt_f32_e32 vcc, s88, v172
	v_pk_mul_f32 v[194:195], v[200:201], v[214:215] op_sel_hi:[1,0]
	v_pk_mul_f32 v[192:193], v[202:203], v[214:215] op_sel_hi:[1,0]
	v_cndmask_b32_e32 v172, v172, v173, vcc
	v_rsq_f32_e32 v172, v172
	v_pk_mul_f32 v[196:197], v[196:197], v[214:215] op_sel_hi:[1,0]
	v_pk_mul_f32 v[200:201], v[204:205], v[214:215] op_sel_hi:[1,0]
	v_cvt_pk_bf16_f32 v192, v192, v193
	v_mul_f32_e32 v173, 0x45800000, v172
	v_cndmask_b32_e32 v172, v172, v173, vcc
	v_mul_f32_e32 v172, v191, v172
	v_pk_mul_f32 v[142:143], v[142:143], v[172:173] op_sel_hi:[1,0]
	v_pk_mul_f32 v[140:141], v[140:141], v[172:173] op_sel_hi:[1,0]
	v_pk_mul_f32 v[170:171], v[138:139], v[172:173] op_sel_hi:[1,0]
	v_pk_mul_f32 v[138:139], v[136:137], v[172:173] op_sel_hi:[1,0]
	v_cvt_pk_bf16_f32 v193, v194, v195
	v_cvt_pk_bf16_f32 v194, v200, v201
	v_cvt_pk_bf16_f32 v195, v196, v197
	v_cvt_pk_bf16_f32 v136, v140, v141
	v_cvt_pk_bf16_f32 v137, v142, v143
	v_cvt_pk_bf16_f32 v138, v138, v139
	v_cvt_pk_bf16_f32 v139, v170, v171
	v_pk_mul_f32 v[128:129], v[0:1], v[128:129]
	global_store_dwordx4 v[198:199], v[192:195], off
	v_pk_mul_f32 v[196:197], v[210:211], v[214:215] op_sel_hi:[1,0]
	v_pk_mul_f32 v[200:201], v[212:213], v[214:215] op_sel_hi:[1,0]
	v_pk_mul_f32 v[194:195], v[206:207], v[214:215] op_sel_hi:[1,0]
	v_pk_mul_f32 v[192:193], v[208:209], v[214:215] op_sel_hi:[1,0]
	global_store_dwordx4 v[168:169], v[136:139], off
	v_pk_mul_f32 v[134:135], v[134:135], v[172:173] op_sel_hi:[1,0]
	v_pk_mul_f32 v[132:133], v[132:133], v[172:173] op_sel_hi:[1,0]
	v_pk_mul_f32 v[136:137], v[130:131], v[172:173] op_sel_hi:[1,0]
	v_pk_mul_f32 v[130:131], v[128:129], v[172:173] op_sel_hi:[1,0]
	v_cvt_pk_bf16_f32 v192, v192, v193
	v_cvt_pk_bf16_f32 v193, v194, v195
	v_cvt_pk_bf16_f32 v194, v200, v201
	v_cvt_pk_bf16_f32 v195, v196, v197
	v_cvt_pk_bf16_f32 v128, v132, v133
	v_cvt_pk_bf16_f32 v129, v134, v135
	v_cvt_pk_bf16_f32 v130, v130, v131
	v_cvt_pk_bf16_f32 v131, v136, v137
	global_store_dwordx4 v[198:199], v[192:195], off offset:64
